# up-GEMM HID stores marked nt (streaming) so the residual stream stays cache resident (on top of v23)
# baseline (speedup 1.0000x reference)
.LBB0_1174:
	v_mul_f32_e32 v151, 0xbfb8aa3b, v126
	v_exp_f32_e32 v151, v151
	v_readlane_b32 s0, v250, 13
	v_lshl_or_b32 v142, s2, 7, v148
	v_readlane_b32 s1, v250, 14
	v_add_f32_e32 v151, 1.0, v151
	v_rcp_f32_e32 v151, v151
	v_lshl_add_u32 v150, s4, 8, v146
	v_ashrrev_i32_e32 v143, 31, v142
	v_mov_b64_e32 v[140:141], s[0:1]
	v_mul_f32_e32 v126, v126, v151
	v_mul_f32_e32 v122, v126, v122
	v_mul_f32_e32 v126, 0xbfb8aa3b, v127
	v_exp_f32_e32 v126, v126
	s_movk_i32 s2, 0x1600
	v_mad_i64_i32 v[144:145], s[0:1], v150, s2, v[140:141]
	v_add_f32_e32 v126, 1.0, v126
	v_rcp_f32_e32 v126, v126
	v_lshlrev_b64 v[142:143], 1, v[142:143]
	v_lshl_add_u64 v[144:145], v[144:145], 0, v[142:143]
	v_readlane_b32 s18, v249, 56
	v_mul_f32_e32 v126, v127, v126
	v_mul_f32_e32 v123, v126, v123
	v_cvt_pk_bf16_f32 v122, v122, v123
	v_mul_f32_e32 v123, 0xbfb8aa3b, v128
	v_exp_f32_e32 v123, v123
	s_andn2_b64 vcc, exec, s[38:39]
	v_readlane_b32 s19, v249, 57
	v_add_f32_e32 v123, 1.0, v123
	v_rcp_f32_e32 v123, v123
	s_nop 0
	v_mul_f32_e32 v123, v128, v123
	v_mul_f32_e32 v123, v123, v124
	v_mul_f32_e32 v124, 0xbfb8aa3b, v129
	v_exp_f32_e32 v124, v124
	s_nop 0
	v_add_f32_e32 v124, 1.0, v124
	v_rcp_f32_e32 v124, v124
	s_nop 0
	v_mul_f32_e32 v124, v129, v124
	v_mul_f32_e32 v124, v124, v125
	v_cvt_pk_bf16_f32 v123, v123, v124
	v_mul_f32_e32 v124, 0xbfb8aa3b, v118
	v_exp_f32_e32 v124, v124
	s_nop 0
	v_add_f32_e32 v124, 1.0, v124
	v_rcp_f32_e32 v124, v124
	s_nop 0
	v_mul_f32_e32 v118, v118, v124
	v_mul_f32_e32 v114, v118, v114
	v_mul_f32_e32 v118, 0xbfb8aa3b, v119
	v_exp_f32_e32 v118, v118
	s_nop 0
	v_add_f32_e32 v118, 1.0, v118
	v_rcp_f32_e32 v118, v118
	s_nop 0
	v_mul_f32_e32 v118, v119, v118
	v_mul_f32_e32 v115, v118, v115
	v_cvt_pk_bf16_f32 v124, v114, v115
	v_mul_f32_e32 v114, 0xbfb8aa3b, v120
	v_exp_f32_e32 v114, v114
	v_mul_f32_e32 v115, 0xbfb8aa3b, v121
	v_exp_f32_e32 v115, v115
	v_add_f32_e32 v114, 1.0, v114
	v_rcp_f32_e32 v114, v114
	v_add_f32_e32 v115, 1.0, v115
	v_rcp_f32_e32 v115, v115
	v_mul_f32_e32 v114, v120, v114
	v_mul_f32_e32 v114, v114, v116
	v_mul_f32_e32 v116, 0xbfb8aa3b, v110
	v_exp_f32_e32 v116, v116
	v_mul_f32_e32 v115, v121, v115
	v_mul_f32_e32 v115, v115, v117
	v_cvt_pk_bf16_f32 v125, v114, v115
	v_add_f32_e32 v116, 1.0, v116
	v_rcp_f32_e32 v116, v116
	global_store_dwordx4 v[144:145], v[122:125], off nt
	v_or_b32_e32 v114, 16, v150
	v_mad_i64_i32 v[114:115], s[0:1], v114, s2, v[140:141]
	v_mul_f32_e32 v110, v110, v116
	v_mul_f32_e32 v106, v110, v106
	v_mul_f32_e32 v110, 0xbfb8aa3b, v111
	v_exp_f32_e32 v110, v110
	v_lshl_add_u64 v[114:115], v[114:115], 0, v[142:143]
	v_add_f32_e32 v110, 1.0, v110
	v_rcp_f32_e32 v110, v110
	s_nop 0
	v_mul_f32_e32 v110, v111, v110
	v_mul_f32_e32 v107, v110, v107
	v_cvt_pk_bf16_f32 v106, v106, v107
	v_mul_f32_e32 v107, 0xbfb8aa3b, v112
	v_exp_f32_e32 v107, v107
	s_nop 0
	v_add_f32_e32 v107, 1.0, v107
	v_rcp_f32_e32 v107, v107
	s_nop 0
	v_mul_f32_e32 v107, v112, v107
	v_mul_f32_e32 v107, v107, v108
	v_mul_f32_e32 v108, 0xbfb8aa3b, v113
	v_exp_f32_e32 v108, v108
	s_nop 0
	v_add_f32_e32 v108, 1.0, v108
	v_rcp_f32_e32 v108, v108
	s_nop 0
	v_mul_f32_e32 v108, v113, v108
	v_mul_f32_e32 v108, v108, v109
	v_cvt_pk_bf16_f32 v107, v107, v108
	v_mul_f32_e32 v108, 0xbfb8aa3b, v102
	v_exp_f32_e32 v108, v108
	s_nop 0
	v_add_f32_e32 v108, 1.0, v108
	v_rcp_f32_e32 v108, v108
	s_nop 0
	v_mul_f32_e32 v102, v102, v108
	v_mul_f32_e32 v98, v102, v98
	v_mul_f32_e32 v102, 0xbfb8aa3b, v103
	v_exp_f32_e32 v102, v102
	s_nop 0
	v_add_f32_e32 v102, 1.0, v102
	v_rcp_f32_e32 v102, v102
	s_nop 0
	v_mul_f32_e32 v102, v103, v102
	v_mul_f32_e32 v99, v102, v99
	v_cvt_pk_bf16_f32 v108, v98, v99
	v_mul_f32_e32 v98, 0xbfb8aa3b, v104
	v_exp_f32_e32 v98, v98
	v_mul_f32_e32 v99, 0xbfb8aa3b, v105
	v_exp_f32_e32 v99, v99
	v_add_f32_e32 v98, 1.0, v98
	v_rcp_f32_e32 v98, v98
	v_add_f32_e32 v99, 1.0, v99
	v_rcp_f32_e32 v99, v99
	v_mul_f32_e32 v98, v104, v98
	v_mul_f32_e32 v98, v98, v100
	v_mul_f32_e32 v100, 0xbfb8aa3b, v94
	v_exp_f32_e32 v100, v100
	v_mul_f32_e32 v99, v105, v99
	v_mul_f32_e32 v99, v99, v101
	v_cvt_pk_bf16_f32 v109, v98, v99
	v_add_f32_e32 v100, 1.0, v100
	v_rcp_f32_e32 v100, v100
	global_store_dwordx4 v[114:115], v[106:109], off nt
	v_or_b32_e32 v98, 32, v150
	v_mad_i64_i32 v[98:99], s[0:1], v98, s2, v[140:141]
	v_mul_f32_e32 v94, v94, v100
	v_mul_f32_e32 v90, v94, v90
	v_mul_f32_e32 v94, 0xbfb8aa3b, v95
	v_exp_f32_e32 v94, v94
	v_lshl_add_u64 v[98:99], v[98:99], 0, v[142:143]
	v_add_f32_e32 v94, 1.0, v94
	v_rcp_f32_e32 v94, v94
	s_nop 0
	v_mul_f32_e32 v94, v95, v94
	v_mul_f32_e32 v91, v94, v91
	v_cvt_pk_bf16_f32 v90, v90, v91
	v_mul_f32_e32 v91, 0xbfb8aa3b, v96
	v_exp_f32_e32 v91, v91
	s_nop 0
	v_add_f32_e32 v91, 1.0, v91
	v_rcp_f32_e32 v91, v91
	s_nop 0
	v_mul_f32_e32 v91, v96, v91
	v_mul_f32_e32 v91, v91, v92
	v_mul_f32_e32 v92, 0xbfb8aa3b, v97
	v_exp_f32_e32 v92, v92
	s_nop 0
	v_add_f32_e32 v92, 1.0, v92
	v_rcp_f32_e32 v92, v92
	s_nop 0
	v_mul_f32_e32 v92, v97, v92
	v_mul_f32_e32 v92, v92, v93
	v_cvt_pk_bf16_f32 v91, v91, v92
	v_mul_f32_e32 v92, 0xbfb8aa3b, v86
	v_exp_f32_e32 v92, v92
	s_nop 0
	v_add_f32_e32 v92, 1.0, v92
	v_rcp_f32_e32 v92, v92
	s_nop 0
	v_mul_f32_e32 v86, v86, v92
	v_mul_f32_e32 v82, v86, v82
	v_mul_f32_e32 v86, 0xbfb8aa3b, v87
	v_exp_f32_e32 v86, v86
	s_nop 0
	v_add_f32_e32 v86, 1.0, v86
	v_rcp_f32_e32 v86, v86
	s_nop 0
	v_mul_f32_e32 v86, v87, v86
	v_mul_f32_e32 v83, v86, v83
	v_cvt_pk_bf16_f32 v92, v82, v83
	v_mul_f32_e32 v82, 0xbfb8aa3b, v88
	v_exp_f32_e32 v82, v82
	v_mul_f32_e32 v83, 0xbfb8aa3b, v89
	v_exp_f32_e32 v83, v83
	v_add_f32_e32 v82, 1.0, v82
	v_rcp_f32_e32 v82, v82
	v_add_f32_e32 v83, 1.0, v83
	v_rcp_f32_e32 v83, v83
	v_mul_f32_e32 v82, v88, v82
	v_mul_f32_e32 v82, v82, v84
	v_mul_f32_e32 v84, 0xbfb8aa3b, v78
	v_exp_f32_e32 v84, v84
	v_mul_f32_e32 v83, v89, v83
	v_mul_f32_e32 v83, v83, v85
	v_cvt_pk_bf16_f32 v93, v82, v83
	v_add_f32_e32 v84, 1.0, v84
	v_rcp_f32_e32 v84, v84
	global_store_dwordx4 v[98:99], v[90:93], off nt
	v_or_b32_e32 v82, 48, v150
	v_mad_i64_i32 v[82:83], s[0:1], v82, s2, v[140:141]
	v_mul_f32_e32 v78, v78, v84
	v_mul_f32_e32 v74, v78, v74
	v_mul_f32_e32 v78, 0xbfb8aa3b, v79
	v_exp_f32_e32 v78, v78
	v_lshl_add_u64 v[82:83], v[82:83], 0, v[142:143]
	v_add_f32_e32 v78, 1.0, v78
	v_rcp_f32_e32 v78, v78
	s_nop 0
	v_mul_f32_e32 v78, v79, v78
	v_mul_f32_e32 v75, v78, v75
	v_cvt_pk_bf16_f32 v74, v74, v75
	v_mul_f32_e32 v75, 0xbfb8aa3b, v80
	v_exp_f32_e32 v75, v75
	s_nop 0
	v_add_f32_e32 v75, 1.0, v75
	v_rcp_f32_e32 v75, v75
	s_nop 0
	v_mul_f32_e32 v75, v80, v75
	v_mul_f32_e32 v75, v75, v76
	v_mul_f32_e32 v76, 0xbfb8aa3b, v81
	v_exp_f32_e32 v76, v76
	s_nop 0
	v_add_f32_e32 v76, 1.0, v76
	v_rcp_f32_e32 v76, v76
	s_nop 0
	v_mul_f32_e32 v76, v81, v76
	v_mul_f32_e32 v76, v76, v77
	v_cvt_pk_bf16_f32 v75, v75, v76
	v_mul_f32_e32 v76, 0xbfb8aa3b, v70
	v_exp_f32_e32 v76, v76
	s_nop 0
	v_add_f32_e32 v76, 1.0, v76
	v_rcp_f32_e32 v76, v76
	s_nop 0
	v_mul_f32_e32 v70, v70, v76
	v_mul_f32_e32 v66, v70, v66
	v_mul_f32_e32 v70, 0xbfb8aa3b, v71
	v_exp_f32_e32 v70, v70
	s_nop 0
	v_add_f32_e32 v70, 1.0, v70
	v_rcp_f32_e32 v70, v70
	s_nop 0
	v_mul_f32_e32 v70, v71, v70
	v_mul_f32_e32 v67, v70, v67
	v_cvt_pk_bf16_f32 v76, v66, v67
	v_mul_f32_e32 v66, 0xbfb8aa3b, v72
	v_exp_f32_e32 v66, v66
	v_mul_f32_e32 v67, 0xbfb8aa3b, v73
	v_exp_f32_e32 v67, v67
	v_add_f32_e32 v66, 1.0, v66
	v_rcp_f32_e32 v66, v66
	v_add_f32_e32 v67, 1.0, v67
	v_rcp_f32_e32 v67, v67
	v_mul_f32_e32 v66, v72, v66
	v_mul_f32_e32 v66, v66, v68
	v_mul_f32_e32 v68, 0xbfb8aa3b, v62
	v_exp_f32_e32 v68, v68
	v_mul_f32_e32 v67, v73, v67
	v_mul_f32_e32 v67, v67, v69
	v_cvt_pk_bf16_f32 v77, v66, v67
	v_add_f32_e32 v68, 1.0, v68
	v_rcp_f32_e32 v68, v68
	global_store_dwordx4 v[82:83], v[74:77], off nt
	v_add_u32_e32 v66, 0x80, v150
	v_mad_i64_i32 v[66:67], s[0:1], v66, s2, v[140:141]
	v_mul_f32_e32 v62, v62, v68
	v_mul_f32_e32 v58, v62, v58
	v_mul_f32_e32 v62, 0xbfb8aa3b, v63
	v_exp_f32_e32 v62, v62
	v_lshl_add_u64 v[66:67], v[66:67], 0, v[142:143]
	v_add_f32_e32 v62, 1.0, v62
	v_rcp_f32_e32 v62, v62
	s_nop 0
	v_mul_f32_e32 v62, v63, v62
	v_mul_f32_e32 v59, v62, v59
	v_cvt_pk_bf16_f32 v58, v58, v59
	v_mul_f32_e32 v59, 0xbfb8aa3b, v64
	v_exp_f32_e32 v59, v59
	s_nop 0
	v_add_f32_e32 v59, 1.0, v59
	v_rcp_f32_e32 v59, v59
	s_nop 0
	v_mul_f32_e32 v59, v64, v59
	v_mul_f32_e32 v59, v59, v60
	v_mul_f32_e32 v60, 0xbfb8aa3b, v65
	v_exp_f32_e32 v60, v60
	s_nop 0
	v_add_f32_e32 v60, 1.0, v60
	v_rcp_f32_e32 v60, v60
	s_nop 0
	v_mul_f32_e32 v60, v65, v60
	v_mul_f32_e32 v60, v60, v61
	v_cvt_pk_bf16_f32 v59, v59, v60
	v_mul_f32_e32 v60, 0xbfb8aa3b, v54
	v_exp_f32_e32 v60, v60
	s_nop 0
	v_add_f32_e32 v60, 1.0, v60
	v_rcp_f32_e32 v60, v60
	s_nop 0
	v_mul_f32_e32 v54, v54, v60
	v_mul_f32_e32 v50, v54, v50
	v_mul_f32_e32 v54, 0xbfb8aa3b, v55
	v_exp_f32_e32 v54, v54
	s_nop 0
	v_add_f32_e32 v54, 1.0, v54
	v_rcp_f32_e32 v54, v54
	s_nop 0
	v_mul_f32_e32 v54, v55, v54
	v_mul_f32_e32 v51, v54, v51
	v_cvt_pk_bf16_f32 v60, v50, v51
	v_mul_f32_e32 v50, 0xbfb8aa3b, v56
	v_exp_f32_e32 v50, v50
	v_mul_f32_e32 v51, 0xbfb8aa3b, v57
	v_exp_f32_e32 v51, v51
	v_add_f32_e32 v50, 1.0, v50
	v_rcp_f32_e32 v50, v50
	v_add_f32_e32 v51, 1.0, v51
	v_rcp_f32_e32 v51, v51
	v_mul_f32_e32 v50, v56, v50
	v_mul_f32_e32 v50, v50, v52
	v_mul_f32_e32 v52, 0xbfb8aa3b, v46
	v_exp_f32_e32 v52, v52
	v_mul_f32_e32 v51, v57, v51
	v_mul_f32_e32 v51, v51, v53
	v_cvt_pk_bf16_f32 v61, v50, v51
	v_add_f32_e32 v52, 1.0, v52
	v_rcp_f32_e32 v52, v52
	global_store_dwordx4 v[66:67], v[58:61], off nt
	v_add_u32_e32 v50, 0x90, v150
	v_mad_i64_i32 v[50:51], s[0:1], v50, s2, v[140:141]
	v_mul_f32_e32 v46, v46, v52
	v_mul_f32_e32 v42, v46, v42
	v_mul_f32_e32 v46, 0xbfb8aa3b, v47
	v_exp_f32_e32 v46, v46
	v_lshl_add_u64 v[50:51], v[50:51], 0, v[142:143]
	v_add_f32_e32 v46, 1.0, v46
	v_rcp_f32_e32 v46, v46
	s_nop 0
	v_mul_f32_e32 v46, v47, v46
	v_mul_f32_e32 v43, v46, v43
	v_cvt_pk_bf16_f32 v42, v42, v43
	v_mul_f32_e32 v43, 0xbfb8aa3b, v48
	v_exp_f32_e32 v43, v43
	s_nop 0
	v_add_f32_e32 v43, 1.0, v43
	v_rcp_f32_e32 v43, v43
	s_nop 0
	v_mul_f32_e32 v43, v48, v43
	v_mul_f32_e32 v43, v43, v44
	v_mul_f32_e32 v44, 0xbfb8aa3b, v49
	v_exp_f32_e32 v44, v44
	s_nop 0
	v_add_f32_e32 v44, 1.0, v44
	v_rcp_f32_e32 v44, v44
	s_nop 0
	v_mul_f32_e32 v44, v49, v44
	v_mul_f32_e32 v44, v44, v45
	v_cvt_pk_bf16_f32 v43, v43, v44
	v_mul_f32_e32 v44, 0xbfb8aa3b, v38
	v_exp_f32_e32 v44, v44
	s_nop 0
	v_add_f32_e32 v44, 1.0, v44
	v_rcp_f32_e32 v44, v44
	s_nop 0
	v_mul_f32_e32 v38, v38, v44
	v_mul_f32_e32 v34, v38, v34
	v_mul_f32_e32 v38, 0xbfb8aa3b, v39
	v_exp_f32_e32 v38, v38
	s_nop 0
	v_add_f32_e32 v38, 1.0, v38
	v_rcp_f32_e32 v38, v38
	s_nop 0
	v_mul_f32_e32 v38, v39, v38
	v_mul_f32_e32 v35, v38, v35
	v_cvt_pk_bf16_f32 v44, v34, v35
	v_mul_f32_e32 v34, 0xbfb8aa3b, v40
	v_exp_f32_e32 v34, v34
	v_mul_f32_e32 v35, 0xbfb8aa3b, v41
	v_exp_f32_e32 v35, v35
	v_add_f32_e32 v34, 1.0, v34
	v_rcp_f32_e32 v34, v34
	v_add_f32_e32 v35, 1.0, v35
	v_rcp_f32_e32 v35, v35
	v_mul_f32_e32 v34, v40, v34
	v_mul_f32_e32 v34, v34, v36
	v_mul_f32_e32 v36, 0xbfb8aa3b, v30
	v_exp_f32_e32 v36, v36
	v_mul_f32_e32 v35, v41, v35
	v_mul_f32_e32 v35, v35, v37
	v_cvt_pk_bf16_f32 v45, v34, v35
	v_add_f32_e32 v36, 1.0, v36
	v_rcp_f32_e32 v36, v36
	global_store_dwordx4 v[50:51], v[42:45], off nt
	v_add_u32_e32 v34, 0xa0, v150
	v_mad_i64_i32 v[34:35], s[0:1], v34, s2, v[140:141]
	v_mul_f32_e32 v30, v30, v36
	v_mul_f32_e32 v26, v30, v26
	v_mul_f32_e32 v30, 0xbfb8aa3b, v31
	v_exp_f32_e32 v30, v30
	v_lshl_add_u64 v[34:35], v[34:35], 0, v[142:143]
	v_add_f32_e32 v30, 1.0, v30
	v_rcp_f32_e32 v30, v30
	s_nop 0
	v_mul_f32_e32 v30, v31, v30
	v_mul_f32_e32 v27, v30, v27
	v_cvt_pk_bf16_f32 v26, v26, v27
	v_mul_f32_e32 v27, 0xbfb8aa3b, v32
	v_exp_f32_e32 v27, v27
	s_nop 0
	v_add_f32_e32 v27, 1.0, v27
	v_rcp_f32_e32 v27, v27
	s_nop 0
	v_mul_f32_e32 v27, v32, v27
	v_mul_f32_e32 v27, v27, v28
	v_mul_f32_e32 v28, 0xbfb8aa3b, v33
	v_exp_f32_e32 v28, v28
	s_nop 0
	v_add_f32_e32 v28, 1.0, v28
	v_rcp_f32_e32 v28, v28
	s_nop 0
	v_mul_f32_e32 v28, v33, v28
	v_mul_f32_e32 v28, v28, v29
	v_cvt_pk_bf16_f32 v27, v27, v28
	v_mul_f32_e32 v28, 0xbfb8aa3b, v22
	v_exp_f32_e32 v28, v28
	s_nop 0
	v_add_f32_e32 v28, 1.0, v28
	v_rcp_f32_e32 v28, v28
	s_nop 0
	v_mul_f32_e32 v22, v22, v28
	v_mul_f32_e32 v18, v22, v18
	v_mul_f32_e32 v22, 0xbfb8aa3b, v23
	v_exp_f32_e32 v22, v22
	s_nop 0
	v_add_f32_e32 v22, 1.0, v22
	v_rcp_f32_e32 v22, v22
	s_nop 0
	v_mul_f32_e32 v22, v23, v22
	v_mul_f32_e32 v19, v22, v19
	v_cvt_pk_bf16_f32 v28, v18, v19
	v_mul_f32_e32 v18, 0xbfb8aa3b, v24
	v_exp_f32_e32 v18, v18
	v_mul_f32_e32 v19, 0xbfb8aa3b, v25
	v_exp_f32_e32 v19, v19
	v_add_f32_e32 v18, 1.0, v18
	v_rcp_f32_e32 v18, v18
	v_add_f32_e32 v19, 1.0, v19
	v_rcp_f32_e32 v19, v19
	v_mul_f32_e32 v18, v24, v18
	v_mul_f32_e32 v18, v18, v20
	v_mul_f32_e32 v20, 0xbfb8aa3b, v14
	v_exp_f32_e32 v20, v20
	v_mul_f32_e32 v19, v25, v19
	v_mul_f32_e32 v19, v19, v21
	v_cvt_pk_bf16_f32 v29, v18, v19
	v_add_f32_e32 v20, 1.0, v20
	v_rcp_f32_e32 v20, v20
	global_store_dwordx4 v[34:35], v[26:29], off nt
	v_add_u32_e32 v18, 0xb0, v150
	v_mad_i64_i32 v[18:19], s[0:1], v18, s2, v[140:141]
	v_mul_f32_e32 v14, v14, v20
	v_mul_f32_e32 v10, v14, v10
	v_mul_f32_e32 v14, 0xbfb8aa3b, v15
	v_exp_f32_e32 v14, v14
	v_lshl_add_u64 v[18:19], v[18:19], 0, v[142:143]
	s_mov_b64 s[0:1], -1
	v_add_f32_e32 v14, 1.0, v14
	v_rcp_f32_e32 v14, v14
	s_nop 0
	v_mul_f32_e32 v14, v15, v14
	v_mul_f32_e32 v11, v14, v11
	v_cvt_pk_bf16_f32 v10, v10, v11
	v_mul_f32_e32 v11, 0xbfb8aa3b, v16
	v_exp_f32_e32 v11, v11
	s_nop 0
	v_add_f32_e32 v11, 1.0, v11
	v_rcp_f32_e32 v11, v11
	s_nop 0
	v_mul_f32_e32 v11, v16, v11
	v_mul_f32_e32 v11, v11, v12
	v_mul_f32_e32 v12, 0xbfb8aa3b, v17
	v_exp_f32_e32 v12, v12
	s_nop 0
	v_add_f32_e32 v12, 1.0, v12
	v_rcp_f32_e32 v12, v12
	s_nop 0
	v_mul_f32_e32 v12, v17, v12
	v_mul_f32_e32 v12, v12, v13
	v_cvt_pk_bf16_f32 v11, v11, v12
	v_mul_f32_e32 v12, 0xbfb8aa3b, v6
	v_exp_f32_e32 v12, v12
	s_nop 0
	v_add_f32_e32 v12, 1.0, v12
	v_rcp_f32_e32 v12, v12
	s_nop 0
	v_mul_f32_e32 v6, v6, v12
	v_mul_f32_e32 v2, v6, v2
	v_mul_f32_e32 v6, 0xbfb8aa3b, v7
	v_exp_f32_e32 v6, v6
	s_nop 0
	v_add_f32_e32 v6, 1.0, v6
	v_rcp_f32_e32 v6, v6
	s_nop 0
	v_mul_f32_e32 v6, v7, v6
	v_mul_f32_e32 v3, v6, v3
	v_cvt_pk_bf16_f32 v12, v2, v3
	v_mul_f32_e32 v2, 0xbfb8aa3b, v8
	v_mul_f32_e32 v3, 0xbfb8aa3b, v9
	v_exp_f32_e32 v2, v2
	v_exp_f32_e32 v3, v3
	v_add_f32_e32 v2, 1.0, v2
	v_add_f32_e32 v3, 1.0, v3
	v_rcp_f32_e32 v2, v2
	v_rcp_f32_e32 v3, v3
	v_mul_f32_e32 v2, v8, v2
	v_mul_f32_e32 v3, v9, v3
	v_mul_f32_e32 v2, v2, v4
	v_mul_f32_e32 v3, v3, v5
	v_cvt_pk_bf16_f32 v13, v2, v3
	global_store_dwordx4 v[18:19], v[10:13], off nt
	s_cbranch_vccnz .LBB0_1163
	s_andn2_b64 vcc, exec, s[40:41]
	s_cbranch_vccnz .LBB0_1162
	s_barrier
	s_branch .LBB0_1162
